# grid barrier: L1 invalidate hoisted ahead of the spins (overlaps the wait); XCD barrier replaces cg grid sync after phase 0
# speedup vs baseline: 1.0193x; 1.0065x over previous
.LBB0_413:
	s_mov_b64 s[8:9], s[56:57]
	s_load_dword s1, s[8:9], 0x8c
	s_add_i32 s0, s91, 1
	s_mov_b64 s[6:7], -1
	s_waitcnt lgkmcnt(0)
	s_cmp_ge_i32 s0, s1
	s_cbranch_scc1 .LBB0_9
	s_cmp_eq_u32 s91, 0
	s_cbranch_scc1 .Lgb_full
	s_cmp_eq_u32 s91, 32
	s_cbranch_scc1 .Lgb_full
	s_add_i32 s1, s91, -1
	s_and_b32 s1, s1, 7
	s_movk_i32 s2, 0xe1
	s_bitcmp1_b32 s2, s1
	s_cbranch_scc1 .Lgb_start

.LBB0_433:
	s_or_b64 exec, exec, s[16:17]
	v_cvt_f32_u32_e32 v4, v2
	s_waitcnt vmcnt(0)
	v_readfirstlane_b32 s1, v3
	v_sub_u32_e32 v3, 0, v2
	v_rcp_iflag_f32_e32 v4, v4
	v_add_u32_e32 v5, s1, v1
	v_mul_f32_e32 v4, 0x4f7ffffe, v4
	v_cvt_u32_f32_e32 v4, v4
	v_mul_lo_u32 v1, v3, v4
	v_mul_hi_u32 v1, v4, v1
	v_add_u32_e32 v1, v4, v1
	v_mul_hi_u32 v1, v5, v1
	v_mul_lo_u32 v3, v1, v2
	v_sub_u32_e32 v3, v5, v3
	v_add_u32_e32 v4, 1, v1
	v_cmp_ge_u32_e32 vcc, v3, v2
	s_nop 1
	v_cndmask_b32_e32 v1, v1, v4, vcc
	v_sub_u32_e32 v4, v3, v2
	v_cndmask_b32_e32 v3, v3, v4, vcc
	v_add_u32_e32 v4, 1, v1
	v_cmp_ge_u32_e32 vcc, v3, v2
	v_add_u32_e32 v3, 1, v5
	s_nop 0
	v_cndmask_b32_e32 v1, v1, v4, vcc
	v_mul_lo_u32 v4, v2, v1
	v_add_u32_e32 v2, v4, v2
	v_cmp_ne_u32_e32 vcc, v3, v2
	s_and_saveexec_b64 s[4:5], vcc
	s_xor_b64 s[14:15], exec, s[4:5]
	s_cbranch_execz .LBB0_447
	s_waitcnt lgkmcnt(0)
	buffer_inv sc1
	global_load_dword v0, v200, s[12:13] offset:1024 sc1
	s_add_u32 s64, s12, 0x2400
	s_addc_u32 s65, s13, 0
	s_waitcnt vmcnt(0)
	v_cmp_eq_u32_e32 vcc, v0, v1
	s_and_saveexec_b64 s[16:17], vcc
	s_cbranch_execz .LBB0_446
	s_add_u32 s18, s8, 0x1d400200
	s_addc_u32 s19, s9, 0
	s_mov_b32 s1, 1
	s_mov_b64 s[66:67], 0
	s_branch .LBB0_437

.LBB0_446:
	s_or_b64 exec, exec, s[16:17]
	s_waitcnt vmcnt(0)
	s_waitcnt vmcnt(0)
.LBB0_447:
	s_andn2_saveexec_b64 s[4:5], s[14:15]
	s_cbranch_execz .LBB0_467
	s_mov_b64 s[14:15], exec
	buffer_wbl2 sc1
	buffer_inv sc1
	s_waitcnt lgkmcnt(0)
	s_waitcnt vmcnt(0)
	v_mbcnt_lo_u32_b32 v1, s14, 0
	v_mbcnt_hi_u32_b32 v1, s15, v1
	v_cmp_eq_u32_e32 vcc, 0, v1
	s_and_saveexec_b64 s[16:17], vcc
	s_cbranch_execz .LBB0_450
	s_bcnt1_i32_b64 s1, s[14:15]
	v_mov_b32_e32 v2, s1
	v_mov_b32_e32 v3, 0x1d403000
	global_atomic_add v2, v3, v2, s[8:9] offset:1024 sc0

.LBB0_464:
	s_or_b64 exec, exec, s[8:9]
	s_mov_b64 s[8:9], exec
	v_mbcnt_lo_u32_b32 v0, s8, 0
	v_mbcnt_hi_u32_b32 v0, s9, v0
	v_cmp_eq_u32_e32 vcc, 0, v0
	s_waitcnt vmcnt(0)
	s_and_saveexec_b64 s[14:15], vcc
	s_cbranch_execz .LBB0_466
	s_bcnt1_i32_b64 s1, s[8:9]
	v_mov_b32_e32 v0, s1
	global_atomic_add v200, v0, s[12:13] offset:1024
